# late weight-transposition items: the 32 f32 weight loads per item carry the nt (streaming) cache hint so they do not displace the attention outputs the next GEMM reads
# baseline (speedup 1.0000x reference)
; #define LAS __attribute__((address_space(3)))
; DI void transpose_item(const float* W, int ldw, int src0, int len, bf16_t* WT, int ldwt, int dst0, int dstride, const float* csc, const float* gk, LAS float* scr, int kb, int nb, int lane) {
;     const int k0 = 64 * kb, n0 = 32 * nb;
;     const bool okc = (n0 + (lane & 31)) < len;
;     const float cs_ = (csc && okc) ? csc[n0 + (lane & 31)] : 1.f;
;     float tv[32];
; #pragma unroll
;     for (int i = 0; i < 32; ++i) { const int kk = 2 * i + (lane >> 5); tv[i] = okc ? W[(size_t)(k0 + kk) * ldw + src0 + n0 + (lane & 31)] : 0.f; }
.LBB0_680:
	s_or_b64 exec, exec, s[2:3]
	s_ashr_i32 s3, s69, 31
	s_mov_b32 s2, s69
	s_lshl_b64 s[2:3], s[2:3], 2
	s_add_u32 s22, s28, s2
	s_addc_u32 s29, s29, s3
	s_ashr_i32 s79, s78, 31
	s_lshl_b32 s28, s1, 6
	s_ashr_i32 s1, s0, 31
	s_lshl_b64 s[2:3], s[78:79], 2
	s_add_u32 s22, s22, s2
	s_addc_u32 s29, s29, s3
	s_lshl_b64 s[2:3], s[0:1], 2
	s_add_u32 s2, s22, s2
	s_addc_u32 s3, s29, s3
	v_lshlrev_b32_e32 v0, 2, v122
	v_or_b32_e32 v2, s28, v124
	v_lshl_add_u64 v[4:5], s[2:3], 0, v[0:1]
	v_mov_b32_e32 v21, 0
	v_mov_b32_e32 v37, 0
	s_and_saveexec_b64 s[2:3], vcc
	s_cbranch_execz .LBB0_682
	v_mad_i64_i32 v[8:9], s[30:31], v2, s70, 0
	v_lshl_add_u64 v[8:9], v[8:9], 2, v[4:5]
	global_load_dword v37, v[8:9], off nt
.LBB0_682:
	s_or_b64 exec, exec, s[2:3]
	s_and_saveexec_b64 s[2:3], vcc
	s_cbranch_execz .LBB0_684
	v_or_b32_e32 v0, 2, v2
	v_mad_i64_i32 v[8:9], s[30:31], v0, s70, 0
	v_lshl_add_u64 v[8:9], v[8:9], 2, v[4:5]
	global_load_dword v21, v[8:9], off nt
.LBB0_684:
	s_or_b64 exec, exec, s[2:3]
	v_mov_b32_e32 v20, 0
	v_mov_b32_e32 v36, 0
	s_and_saveexec_b64 s[2:3], vcc
	s_cbranch_execz .LBB0_686
	v_or_b32_e32 v0, 4, v2
	v_mad_i64_i32 v[8:9], s[30:31], v0, s70, 0
	v_lshl_add_u64 v[8:9], v[8:9], 2, v[4:5]
	global_load_dword v36, v[8:9], off nt
.LBB0_686:
	s_or_b64 exec, exec, s[2:3]
	s_and_saveexec_b64 s[2:3], vcc
	s_cbranch_execz .LBB0_688
	v_or_b32_e32 v0, 6, v2
	v_mad_i64_i32 v[8:9], s[30:31], v0, s70, 0
	v_lshl_add_u64 v[8:9], v[8:9], 2, v[4:5]
	global_load_dword v20, v[8:9], off nt
.LBB0_688:
	s_or_b64 exec, exec, s[2:3]
	v_mov_b32_e32 v19, 0
	v_mov_b32_e32 v35, 0
	s_and_saveexec_b64 s[2:3], vcc
	s_cbranch_execz .LBB0_690
	v_or_b32_e32 v0, 8, v2
	v_mad_i64_i32 v[8:9], s[30:31], v0, s70, 0
	v_lshl_add_u64 v[8:9], v[8:9], 2, v[4:5]
	global_load_dword v35, v[8:9], off nt
.LBB0_690:
	s_or_b64 exec, exec, s[2:3]
	s_and_saveexec_b64 s[2:3], vcc
	s_cbranch_execz .LBB0_692
	v_or_b32_e32 v0, 10, v2
	v_mad_i64_i32 v[8:9], s[30:31], v0, s70, 0
	v_lshl_add_u64 v[8:9], v[8:9], 2, v[4:5]
	global_load_dword v19, v[8:9], off nt
.LBB0_692:
	s_or_b64 exec, exec, s[2:3]
	v_mov_b32_e32 v18, 0
	v_mov_b32_e32 v34, 0
	s_and_saveexec_b64 s[2:3], vcc
	s_cbranch_execz .LBB0_694
	v_or_b32_e32 v0, 12, v2
	v_mad_i64_i32 v[8:9], s[30:31], v0, s70, 0
	v_lshl_add_u64 v[8:9], v[8:9], 2, v[4:5]
	global_load_dword v34, v[8:9], off nt
.LBB0_694:
	s_or_b64 exec, exec, s[2:3]
	s_and_saveexec_b64 s[2:3], vcc
	s_cbranch_execz .LBB0_696
	v_or_b32_e32 v0, 14, v2
	v_mad_i64_i32 v[8:9], s[30:31], v0, s70, 0
	v_lshl_add_u64 v[8:9], v[8:9], 2, v[4:5]
	global_load_dword v18, v[8:9], off nt
.LBB0_696:
	s_or_b64 exec, exec, s[2:3]
	v_mov_b32_e32 v17, 0
	v_mov_b32_e32 v33, 0
	s_and_saveexec_b64 s[2:3], vcc
	s_cbranch_execz .LBB0_698
	v_or_b32_e32 v0, 16, v2
	v_mad_i64_i32 v[8:9], s[30:31], v0, s70, 0
	v_lshl_add_u64 v[8:9], v[8:9], 2, v[4:5]
	global_load_dword v33, v[8:9], off nt
.LBB0_698:
	s_or_b64 exec, exec, s[2:3]
	s_and_saveexec_b64 s[2:3], vcc
	s_cbranch_execz .LBB0_700
	v_or_b32_e32 v0, 18, v2
	v_mad_i64_i32 v[8:9], s[30:31], v0, s70, 0
	v_lshl_add_u64 v[8:9], v[8:9], 2, v[4:5]
	global_load_dword v17, v[8:9], off nt
.LBB0_700:
	s_or_b64 exec, exec, s[2:3]
	v_mov_b32_e32 v16, 0
	v_mov_b32_e32 v32, 0
	s_and_saveexec_b64 s[2:3], vcc
	s_cbranch_execz .LBB0_702
	v_or_b32_e32 v0, 20, v2
	v_mad_i64_i32 v[8:9], s[30:31], v0, s70, 0
	v_lshl_add_u64 v[8:9], v[8:9], 2, v[4:5]
	global_load_dword v32, v[8:9], off nt
.LBB0_702:
	s_or_b64 exec, exec, s[2:3]
	s_and_saveexec_b64 s[2:3], vcc
	s_cbranch_execz .LBB0_704
	v_or_b32_e32 v0, 22, v2
	v_mad_i64_i32 v[8:9], s[30:31], v0, s70, 0
	v_lshl_add_u64 v[8:9], v[8:9], 2, v[4:5]
	global_load_dword v16, v[8:9], off nt
.LBB0_704:
	s_or_b64 exec, exec, s[2:3]
	v_mov_b32_e32 v15, 0
	v_mov_b32_e32 v31, 0
	s_and_saveexec_b64 s[2:3], vcc
	s_cbranch_execz .LBB0_706
	v_or_b32_e32 v0, 24, v2
	v_mad_i64_i32 v[8:9], s[30:31], v0, s70, 0
	v_lshl_add_u64 v[8:9], v[8:9], 2, v[4:5]
	global_load_dword v31, v[8:9], off nt
.LBB0_706:
	s_or_b64 exec, exec, s[2:3]
	s_and_saveexec_b64 s[2:3], vcc
	s_cbranch_execz .LBB0_708
	v_or_b32_e32 v0, 26, v2
	v_mad_i64_i32 v[8:9], s[30:31], v0, s70, 0
	v_lshl_add_u64 v[8:9], v[8:9], 2, v[4:5]
	global_load_dword v15, v[8:9], off nt
.LBB0_708:
	s_or_b64 exec, exec, s[2:3]
	v_mov_b32_e32 v14, 0
	v_mov_b32_e32 v30, 0
	s_and_saveexec_b64 s[2:3], vcc
	s_cbranch_execz .LBB0_710
	v_or_b32_e32 v0, 28, v2
	v_mad_i64_i32 v[8:9], s[30:31], v0, s70, 0
	v_lshl_add_u64 v[8:9], v[8:9], 2, v[4:5]
	global_load_dword v30, v[8:9], off nt
; DI void transpose_item(const float* W, int ldw, int src0, int len, bf16_t* WT, int ldwt, int dst0, int dstride, const float* csc, const float* gk, LAS float* scr, int kb, int nb, int lane) {
;     ...
;     for (int i = 0; i < 32; ++i) { const int kk = 2 * i + (lane >> 5); tv[i] = okc ? W[(size_t)(k0 + kk) * ldw + src0 + n0 + (lane & 31)] : 0.f; }
.LBB0_710:
	s_or_b64 exec, exec, s[2:3]
	s_and_saveexec_b64 s[2:3], vcc
	s_cbranch_execz .LBB0_712
	v_or_b32_e32 v0, 30, v2
	v_mad_i64_i32 v[8:9], s[30:31], v0, s70, 0
	v_lshl_add_u64 v[8:9], v[8:9], 2, v[4:5]
	global_load_dword v14, v[8:9], off nt
.LBB0_712:
	s_or_b64 exec, exec, s[2:3]
	v_mov_b32_e32 v13, 0
	v_mov_b32_e32 v29, 0
	s_and_saveexec_b64 s[2:3], vcc
	s_cbranch_execz .LBB0_714
	v_or_b32_e32 v0, 32, v2
	v_mad_i64_i32 v[8:9], s[30:31], v0, s70, 0
	v_lshl_add_u64 v[8:9], v[8:9], 2, v[4:5]
	global_load_dword v29, v[8:9], off nt
.LBB0_714:
	s_or_b64 exec, exec, s[2:3]
	s_and_saveexec_b64 s[2:3], vcc
	s_cbranch_execz .LBB0_716
	v_or_b32_e32 v0, 34, v2
	v_mad_i64_i32 v[8:9], s[30:31], v0, s70, 0
	v_lshl_add_u64 v[8:9], v[8:9], 2, v[4:5]
	global_load_dword v13, v[8:9], off nt
.LBB0_716:
	s_or_b64 exec, exec, s[2:3]
	v_mov_b32_e32 v12, 0
	v_mov_b32_e32 v28, 0
	s_and_saveexec_b64 s[2:3], vcc
	s_cbranch_execz .LBB0_718
	v_or_b32_e32 v0, 36, v2
	v_mad_i64_i32 v[8:9], s[30:31], v0, s70, 0
	v_lshl_add_u64 v[8:9], v[8:9], 2, v[4:5]
	global_load_dword v28, v[8:9], off nt
.LBB0_718:
	s_or_b64 exec, exec, s[2:3]
	s_and_saveexec_b64 s[2:3], vcc
	s_cbranch_execz .LBB0_720
	v_or_b32_e32 v0, 38, v2
	v_mad_i64_i32 v[8:9], s[30:31], v0, s70, 0
	v_lshl_add_u64 v[8:9], v[8:9], 2, v[4:5]
	global_load_dword v12, v[8:9], off nt
.LBB0_720:
	s_or_b64 exec, exec, s[2:3]
	v_mov_b32_e32 v11, 0
	v_mov_b32_e32 v27, 0
	s_and_saveexec_b64 s[2:3], vcc
	s_cbranch_execz .LBB0_722
	v_or_b32_e32 v0, 40, v2
	v_mad_i64_i32 v[8:9], s[30:31], v0, s70, 0
	v_lshl_add_u64 v[8:9], v[8:9], 2, v[4:5]
	global_load_dword v27, v[8:9], off nt
.LBB0_722:
	s_or_b64 exec, exec, s[2:3]
	s_and_saveexec_b64 s[2:3], vcc
	s_cbranch_execz .LBB0_724
	v_or_b32_e32 v0, 42, v2
	v_mad_i64_i32 v[8:9], s[30:31], v0, s70, 0
	v_lshl_add_u64 v[8:9], v[8:9], 2, v[4:5]
	global_load_dword v11, v[8:9], off nt
.LBB0_724:
	s_or_b64 exec, exec, s[2:3]
	v_mov_b32_e32 v10, 0
	v_mov_b32_e32 v26, 0
	s_and_saveexec_b64 s[2:3], vcc
	s_cbranch_execz .LBB0_726
	v_or_b32_e32 v0, 44, v2
	v_mad_i64_i32 v[8:9], s[30:31], v0, s70, 0
	v_lshl_add_u64 v[8:9], v[8:9], 2, v[4:5]
	global_load_dword v26, v[8:9], off nt
.LBB0_726:
	s_or_b64 exec, exec, s[2:3]
	s_and_saveexec_b64 s[2:3], vcc
	s_cbranch_execz .LBB0_728
	v_or_b32_e32 v0, 46, v2
	v_mad_i64_i32 v[8:9], s[30:31], v0, s70, 0
	v_lshl_add_u64 v[8:9], v[8:9], 2, v[4:5]
	global_load_dword v10, v[8:9], off nt
.LBB0_728:
	s_or_b64 exec, exec, s[2:3]
	v_mov_b32_e32 v9, 0
	v_mov_b32_e32 v25, 0
	s_and_saveexec_b64 s[2:3], vcc
	s_cbranch_execz .LBB0_730
	v_or_b32_e32 v0, 48, v2
	v_mad_i64_i32 v[22:23], s[30:31], v0, s70, 0
	v_lshl_add_u64 v[22:23], v[22:23], 2, v[4:5]
	global_load_dword v25, v[22:23], off nt
.LBB0_730:
	s_or_b64 exec, exec, s[2:3]
	s_and_saveexec_b64 s[2:3], vcc
	s_cbranch_execz .LBB0_732
	v_or_b32_e32 v0, 50, v2
	v_mad_i64_i32 v[8:9], s[30:31], v0, s70, 0
	v_lshl_add_u64 v[8:9], v[8:9], 2, v[4:5]
	global_load_dword v9, v[8:9], off nt
.LBB0_732:
	s_or_b64 exec, exec, s[2:3]
	v_mov_b32_e32 v8, 0
	v_mov_b32_e32 v24, 0
	s_and_saveexec_b64 s[2:3], vcc
	s_cbranch_execz .LBB0_734
	v_or_b32_e32 v0, 52, v2
	v_mad_i64_i32 v[22:23], s[30:31], v0, s70, 0
	v_lshl_add_u64 v[22:23], v[22:23], 2, v[4:5]
	global_load_dword v24, v[22:23], off nt
.LBB0_734:
	s_or_b64 exec, exec, s[2:3]
	s_and_saveexec_b64 s[2:3], vcc
	s_cbranch_execz .LBB0_736
	v_or_b32_e32 v0, 54, v2
	v_mad_i64_i32 v[22:23], s[30:31], v0, s70, 0
	v_lshl_add_u64 v[22:23], v[22:23], 2, v[4:5]
	global_load_dword v8, v[22:23], off nt
.LBB0_736:
	s_or_b64 exec, exec, s[2:3]
	v_mov_b32_e32 v7, 0
	v_mov_b32_e32 v23, 0
	s_and_saveexec_b64 s[2:3], vcc
	s_cbranch_execz .LBB0_738
	v_or_b32_e32 v0, 56, v2
	v_mad_i64_i32 v[22:23], s[30:31], v0, s70, 0
	v_lshl_add_u64 v[22:23], v[22:23], 2, v[4:5]
	global_load_dword v23, v[22:23], off nt
.LBB0_738:
	s_or_b64 exec, exec, s[2:3]
	s_and_saveexec_b64 s[2:3], vcc
	s_cbranch_execz .LBB0_740
	v_or_b32_e32 v0, 58, v2
	v_mad_i64_i32 v[38:39], s[30:31], v0, s70, 0
	v_lshl_add_u64 v[38:39], v[38:39], 2, v[4:5]
	global_load_dword v7, v[38:39], off nt
.LBB0_740:
	s_or_b64 exec, exec, s[2:3]
	v_mov_b32_e32 v0, 0
	v_mov_b32_e32 v22, 0
	s_and_saveexec_b64 s[2:3], vcc
	s_cbranch_execz .LBB0_742
	v_or_b32_e32 v3, 60, v2
	v_mad_i64_i32 v[38:39], s[30:31], v3, s70, 0
	v_lshl_add_u64 v[38:39], v[38:39], 2, v[4:5]
	global_load_dword v22, v[38:39], off nt
.LBB0_742:
	s_or_b64 exec, exec, s[2:3]
	s_and_saveexec_b64 s[2:3], vcc
	s_cbranch_execz .LBB0_744
	v_or_b32_e32 v0, 62, v2
	v_mad_i64_i32 v[38:39], s[30:31], v0, s70, 0
	v_lshl_add_u64 v[4:5], v[38:39], 2, v[4:5]
	global_load_dword v0, v[4:5], off nt
